# static priority for waves 0-3 raised from 1 to 3
# speedup vs baseline: 1.0094x; 1.0094x over previous
; #define LAS __attribute__((address_space(3)))
; __global__ void __launch_bounds__(512, 2) fwd(Params P) {
;     extern __shared__ __attribute__((aligned(16))) unsigned char shm[];
;     cg::grid_group grid = cg::this_grid();
;     const int lo = P.ph_lo, hi = P.ph_hi;
;     const int tid = threadIdx.x, wave = tid >> 6;
;     unsigned char* ws = P.ws;
;     volatile LAS unsigned* bst = (volatile LAS unsigned*)((LAS unsigned char*)shm + BARST_OFF);
;     if (tid == 0) { bst[0] = 0u; bst[1] = 0u; }
;     __syncthreads();
;     XcdBarrier xbar = xcd_barrier_post((unsigned*)(ws + O_BAR), bst);
_Z3fwd6Params:
	s_load_dword s93, s[0:1], 0x118
	s_load_dwordx4 s[12:15], s[0:1], 0x100
	s_load_dwordx2 s[96:97], s[0:1], 0x110
	s_add_u32 s4, s0, 0x110
	v_and_b32_e32 v214, 0x3ff, v0
	s_mov_b32 s94, s2
	s_addc_u32 s5, s1, 0
	v_readfirstlane_b32 s3, v214
	s_nop 3
	s_cmpk_ge_u32 s3, 0x100
	s_cbranch_scc1 .Lprio_done
	s_setprio 3
